# c24 + DIFF ALiBi K-prime operand: exact 3-way bf16 split by truncation (v_and/v_sub) + v_perm pack, per-step lane masking of the B operand dropped (A operand already zero in lanes>=32): 7 VALU fewer p
# speedup vs baseline: 1.0165x; 1.0017x over previous
.LBB0_1421:
	s_and_b32 s18, s18, 0x3fffffc0
	s_lshl_b32 s18, s18, 2
	s_add_i32 s18, s18, 0
	v_lshlrev_b32_e32 v2, 4, v39
	s_add_i32 s18, s18, 0x12300
	v_lshlrev_b32_e32 v1, 3, v39
	v_and_b32_e32 v2, 0xc0, v2
	v_lshlrev_b32_e32 v39, 1, v39
	v_and_or_b32 v2, v1, 24, v2
	v_and_b32_e32 v39, 32, v39
	v_and_b32_e32 v1, 0x100, v1
	s_cmp_lg_u32 0, -1
	v_or3_b32 v1, v2, v39, v1
	s_cselect_b32 s31, 0, 0
	v_add_u32_e32 v215, s31, v1
	v_max_f32_e32 v1, v5, v5
	v_max_f32_e32 v2, v4, v4
	v_max_f32_e32 v1, v2, v1
	v_max3_f32 v1, v1, v6, v7
	v_max3_f32 v1, v1, v8, v9
	v_max3_f32 v1, v1, v10, v11
	v_max3_f32 v1, v1, v12, v13
	v_max3_f32 v1, v1, v14, v15
	v_max3_f32 v1, v1, v16, v17
	v_max3_f32 v1, v1, v18, v19
	v_max3_f32 v1, v1, v20, v21
	v_max3_f32 v1, v1, v22, v23
	v_max3_f32 v1, v1, v24, v25
	v_max3_f32 v1, v1, v26, v27
	v_max3_f32 v1, v1, v28, v29
	v_max3_f32 v1, v1, v30, v31
	v_max3_f32 v1, v1, v32, v33
	v_max3_f32 v1, v1, v34, v35
	v_mov_b32_e32 v2, v1
	s_nop 1
	v_permlane32_swap_b32_e32 v1, v2
	v_max_f32_e32 v2, v2, v2
	v_max_f32_e32 v1, v1, v1
	v_max_f32_e32 v1, v1, v2
	s_ashr_i32 s31, s19, 31
	v_add_f32_e32 v221, 0, v1
	v_sub_f32_e32 v2, v4, v1
	v_sub_f32_e32 v4, v20, v1
	v_sub_f32_e32 v5, v5, v1
	v_sub_f32_e32 v20, v21, v1
	v_sub_f32_e32 v6, v6, v1
	v_sub_f32_e32 v21, v22, v1
	v_sub_f32_e32 v7, v7, v1
	v_sub_f32_e32 v22, v23, v1
	v_sub_f32_e32 v8, v8, v1
	v_sub_f32_e32 v23, v24, v1
	v_sub_f32_e32 v9, v9, v1
	v_sub_f32_e32 v24, v25, v1
	v_sub_f32_e32 v10, v10, v1
	v_sub_f32_e32 v25, v26, v1
	v_sub_f32_e32 v11, v11, v1
	v_sub_f32_e32 v26, v27, v1
	v_sub_f32_e32 v12, v12, v1
	v_sub_f32_e32 v27, v28, v1
	v_sub_f32_e32 v13, v13, v1
	v_sub_f32_e32 v28, v29, v1
	v_sub_f32_e32 v14, v14, v1
	v_sub_f32_e32 v29, v30, v1
	v_sub_f32_e32 v15, v15, v1
	v_sub_f32_e32 v30, v31, v1
	v_sub_f32_e32 v16, v16, v1
	v_sub_f32_e32 v31, v32, v1
	v_sub_f32_e32 v17, v17, v1
	v_sub_f32_e32 v32, v33, v1
	v_sub_f32_e32 v18, v18, v1
	v_sub_f32_e32 v33, v34, v1
	v_sub_f32_e32 v19, v19, v1
	v_sub_f32_e32 v1, v35, v1
	s_lshr_b32 s31, s31, 26
	v_exp_f32_e32 v96, v2
	v_exp_f32_e32 v80, v4
	v_exp_f32_e32 v97, v5
	v_exp_f32_e32 v81, v20
	v_exp_f32_e32 v98, v6
	v_exp_f32_e32 v82, v21
	v_exp_f32_e32 v99, v7
	v_exp_f32_e32 v83, v22
	v_exp_f32_e32 v100, v8
	v_exp_f32_e32 v84, v23
	v_exp_f32_e32 v101, v9
	v_exp_f32_e32 v85, v24
	v_exp_f32_e32 v102, v10
	v_exp_f32_e32 v86, v25
	v_exp_f32_e32 v103, v11
	v_exp_f32_e32 v87, v26
	v_exp_f32_e32 v104, v12
	v_exp_f32_e32 v88, v27
	v_exp_f32_e32 v105, v13
	v_exp_f32_e32 v89, v28
	v_exp_f32_e32 v106, v14
	v_exp_f32_e32 v90, v29
	v_exp_f32_e32 v107, v15
	v_exp_f32_e32 v91, v30
	v_exp_f32_e32 v108, v16
	v_exp_f32_e32 v92, v31
	v_exp_f32_e32 v109, v17
	v_exp_f32_e32 v93, v32
	v_exp_f32_e32 v110, v18
	v_exp_f32_e32 v94, v33
	v_exp_f32_e32 v111, v19
	v_exp_f32_e32 v95, v1
	s_add_i32 s19, s19, s31
	s_waitcnt vmcnt(0)
	v_mov_b32_e32 v14, v3
	v_mov_b32_e32 v15, v3
	s_ashr_i32 s31, s19, 6
	v_lshl_add_u64 v[190:191], s[34:35], 0, v[36:37]
	v_lshl_add_u32 v213, v38, 2, s18
	v_lshl_add_u32 v212, v0, 2, s18
	v_lshl_add_u64 v[194:195], s[40:41], 0, v[36:37]
	v_mov_b32_e32 v0, v3
	v_mov_b32_e32 v1, v3
	v_mov_b32_e32 v2, v3
	v_mov_b32_e32 v4, v3
	v_mov_b32_e32 v5, v3
	v_mov_b32_e32 v6, v3
	v_mov_b32_e32 v7, v3
	v_mov_b32_e32 v8, v3
	v_mov_b32_e32 v9, v3
	v_mov_b32_e32 v10, v3
	v_mov_b32_e32 v11, v3
	v_mov_b32_e32 v12, v3
	v_mov_b32_e32 v13, v3
	v_mov_b64_e32 v[30:31], v[14:15]
	v_mov_b64_e32 v[46:47], v[14:15]
	v_mov_b64_e32 v[62:63], v[14:15]
	v_mov_b64_e32 v[78:79], v[14:15]
	s_mov_b32 s44, 2
	s_mov_b32 s45, 4
	s_mov_b32 s69, 1
	s_mov_b32 s54, 0
	s_sub_i32 s19, 0, s31
	s_sub_i32 s64, 2, s31
	v_mov_b32_e32 v214, 0
	v_mov_b32_e32 v222, 1.0
	s_movk_i32 s65, 0x80
	v_mov_b64_e32 v[28:29], v[12:13]
	v_mov_b64_e32 v[26:27], v[10:11]
	v_mov_b64_e32 v[24:25], v[8:9]
	v_mov_b64_e32 v[22:23], v[6:7]
	v_mov_b64_e32 v[20:21], v[4:5]
	v_mov_b64_e32 v[18:19], v[2:3]
	v_mov_b64_e32 v[16:17], v[0:1]
	v_mov_b64_e32 v[44:45], v[12:13]
	v_mov_b64_e32 v[42:43], v[10:11]
	v_mov_b64_e32 v[40:41], v[8:9]
	v_mov_b64_e32 v[38:39], v[6:7]
	v_mov_b64_e32 v[36:37], v[4:5]
	v_mov_b64_e32 v[34:35], v[2:3]
	v_mov_b64_e32 v[32:33], v[0:1]
	v_mov_b64_e32 v[60:61], v[12:13]
	v_mov_b64_e32 v[58:59], v[10:11]
	v_mov_b64_e32 v[56:57], v[8:9]
	v_mov_b64_e32 v[54:55], v[6:7]
	v_mov_b64_e32 v[52:53], v[4:5]
	v_mov_b64_e32 v[50:51], v[2:3]
	v_mov_b64_e32 v[48:49], v[0:1]
	v_mov_b64_e32 v[76:77], v[12:13]
	v_mov_b64_e32 v[74:75], v[10:11]
	v_mov_b64_e32 v[72:73], v[8:9]
	v_mov_b64_e32 v[70:71], v[6:7]
	v_mov_b64_e32 v[68:69], v[4:5]
	v_mov_b64_e32 v[66:67], v[2:3]
	v_mov_b64_e32 v[64:65], v[0:1]
	s_mov_b32 s99, 0x07060302
	s_waitcnt vmcnt(0)
.LBB0_1422:
	s_barrier
	s_lshl_b32 s18, s44, 14
	s_add_i32 s52, s81, s18
	s_mov_b32 m0, s52
	v_lshl_add_u64 v[0:1], v[194:195], 0, s[14:15]
	global_load_lds_dwordx4 v[194:195], off
	s_add_i32 m0, s52, 0x2000
	s_mul_i32 s52, s54, 0x2100
	s_add_i32 s52, s22, s52
	global_load_lds_dwordx4 v[0:1], off
	s_add_i32 m0, s52, 0xc000
	s_add_i32 s52, s45, -1
	s_cmp_lt_u32 s52, s2
	s_cselect_b32 s55, s52, s3
	s_lshl_b32 s56, s55, 6
	v_mad_u64_u32 v[0:1], s[52:53], s56, v209, v[192:193]
	v_lshl_add_u64 v[0:1], v[0:1], 0, s[10:11]
	global_load_lds_dwordx4 v[0:1], off
	s_mul_i32 s52, s55, 0x60000
	s_mul_hi_u32 s53, s56, 0x1800
	s_mul_i32 s55, s69, 0x2100
	s_add_i32 s71, s55, 0
	s_sub_i32 s55, s65, 64
	v_cvt_f32_u32_e32 v0, s55
	v_add_u32_e32 v166, s71, v220
	v_add_u32_e32 v167, s71, v217
	ds_read_b128 v[4:7], v166 offset:49152
	ds_read_b128 v[8:11], v167 offset:49152
	v_sub_f32_e32 v196, v0, v161
	v_fma_f32 v0, v210, v196, -v221
	v_and_b32_e32 v1, 0xffff0000, v0
	v_sub_f32_e32 v0, v0, v1
	v_and_b32_e32 v2, 0xffff0000, v0
	v_sub_f32_e32 v0, v0, v2
	v_perm_b32 v1, v2, v1, s99
	v_lshrrev_b32_e32 v2, 16, v0
	v_mov_b32_e32 v0, v160
	s_nop 1
	v_mfma_f32_32x32x16_bf16 v[128:143], v[248:251], v[0:3], 0
	v_add_f32_e32 v226, v96, v97
	v_add_f32_e32 v226, v98, v226
	v_add_f32_e32 v226, v99, v226
	v_add_f32_e32 v226, v100, v226
	v_mfma_f32_32x32x16_bf16 v[112:127], v[252:255], v[0:3], 0
	v_add_f32_e32 v1, v101, v226
	v_add_f32_e32 v1, v102, v1
	s_waitcnt lgkmcnt(0)
	v_mfma_f32_32x32x16_bf16 v[128:143], v[8:11], v[156:159], v[128:143]
	v_add_f32_e32 v1, v103, v1
	v_add_f32_e32 v1, v104, v1
	v_add_f32_e32 v1, v105, v1
	v_add_f32_e32 v1, v106, v1
	v_add_f32_e32 v1, v107, v1
	v_add_f32_e32 v1, v108, v1
	v_add_f32_e32 v1, v109, v1
	v_mfma_f32_32x32x16_bf16 v[112:127], v[4:7], v[156:159], v[112:127]
	ds_read_b128 v[4:7], v166 offset:51264
	ds_read_b128 v[8:11], v167 offset:51264
	v_add_f32_e32 v1, v110, v1
	v_add_f32_e32 v1, v111, v1
	v_add_f32_e32 v1, v80, v1
	v_add_f32_e32 v1, v81, v1
	v_add_f32_e32 v1, v82, v1
	v_add_f32_e32 v1, v83, v1
	s_waitcnt lgkmcnt(0)
	v_mfma_f32_32x32x16_bf16 v[128:143], v[8:11], v[152:155], v[128:143]
	v_add_f32_e32 v1, v84, v1
	v_add_f32_e32 v1, v85, v1
	v_add_f32_e32 v1, v86, v1
	v_add_f32_e32 v1, v87, v1
	v_add_f32_e32 v1, v88, v1
	v_add_f32_e32 v1, v89, v1
	v_add_f32_e32 v1, v90, v1
	v_mfma_f32_32x32x16_bf16 v[112:127], v[4:7], v[152:155], v[112:127]
	ds_read_b128 v[4:7], v166 offset:53376
	ds_read_b128 v[8:11], v167 offset:53376
	v_add_f32_e32 v1, v91, v1
	v_add_f32_e32 v1, v92, v1
	v_add_f32_e32 v1, v93, v1
	v_add_f32_e32 v1, v94, v1
	v_add_f32_e32 v223, v95, v1
	v_mov_b32_e32 v224, v223
	s_waitcnt lgkmcnt(0)
	v_mfma_f32_32x32x16_bf16 v[128:143], v[8:11], v[148:151], v[128:143]
	v_permlane32_swap_b32_e32 v223, v224
	v_mfma_f32_32x32x16_bf16 v[112:127], v[4:7], v[148:151], v[112:127]
	ds_read_b128 v[4:7], v166 offset:55488
	ds_read_b128 v[8:11], v167 offset:55488
	v_cvt_pk_bf16_f32 v166, v96, v97
	v_cvt_pk_bf16_f32 v167, v98, v99
	v_cvt_pk_bf16_f32 v168, v100, v101
	v_cvt_pk_bf16_f32 v169, v102, v103
	v_cvt_pk_bf16_f32 v12, v104, v105
	v_cvt_pk_bf16_f32 v13, v106, v107
	s_waitcnt lgkmcnt(0)
	v_mfma_f32_32x32x16_bf16 v[128:143], v[8:11], v[144:147], v[128:143]
	v_cvt_pk_bf16_f32 v14, v108, v109
	v_cvt_pk_bf16_f32 v15, v110, v111
	v_cvt_pk_bf16_f32 v8, v80, v81
	v_cvt_pk_bf16_f32 v9, v82, v83
	v_cvt_pk_bf16_f32 v10, v84, v85
	v_cvt_pk_bf16_f32 v11, v86, v87
	v_mfma_f32_32x32x16_bf16 v[112:127], v[4:7], v[144:147], v[112:127]
	v_cvt_pk_bf16_f32 v4, v88, v89
	v_cvt_pk_bf16_f32 v5, v90, v91
	v_cvt_pk_bf16_f32 v6, v92, v93
	v_cvt_pk_bf16_f32 v7, v94, v95
	v_lshl_add_u32 v1, s54, 14, v215
	ds_read_b64_tr_b16 v[182:183], v1 offset:0
	ds_read_b64_tr_b16 v[184:185], v1 offset:0x800
	ds_read_b64_tr_b16 v[178:179], v1 offset:0x1000
	ds_read_b64_tr_b16 v[180:181], v1 offset:0x1800
	s_add_i32 s70, s45, -3
	s_add_i32 s54, s19, s45
	ds_read_b64_tr_b16 v[174:175], v1 offset:0x2000
	s_cmp_eq_u32 s54, 3
	ds_read_b64_tr_b16 v[176:177], v1 offset:0x2800
	s_cselect_b64 s[54:55], -1, 0
	ds_read_b64_tr_b16 v[170:171], v1 offset:0x3000
	v_cndmask_b32_e64 v2, 0, 1, s[54:55]
	ds_read_b64_tr_b16 v[172:173], v1 offset:0x3800
	s_cmp_lt_i32 s70, s31
	s_cbranch_scc0 .Lold_odd
	v_max3_f32 v245, v128, v129, v130
	v_max3_f32 v246, v112, v113, v114
	v_max3_f32 v245, v245, v131, v132
	v_max3_f32 v246, v246, v115, v116
	v_max3_f32 v245, v245, v133, v134
	v_max3_f32 v246, v246, v117, v118
	v_max3_f32 v245, v245, v135, v136
	v_max3_f32 v246, v246, v119, v120
	v_max3_f32 v245, v245, v137, v138
	v_max3_f32 v246, v246, v121, v122
	v_max3_f32 v245, v245, v139, v140
	v_max3_f32 v246, v246, v123, v124
	v_max3_f32 v245, v245, v141, v142
	v_max3_f32 v246, v246, v125, v126
	v_max_f32_e32 v245, v245, v143
	v_max_f32_e32 v246, v246, v127
	v_max_f32_e32 v245, v245, v246
	v_mov_b32_e32 v246, v245
	s_nop 1
	v_permlane32_swap_b32_e32 v245, v246
	v_max_f32_e32 v245, v245, v246
	v_cmp_ge_f32_e32 vcc, s68, v245
	s_cmp_eq_u64 vcc, exec
	v_mov_b32_e32 v225, 1.0
	s_cbranch_scc0 .Lf_odd_resc

.LBB0_1437:
	s_waitcnt vmcnt(0)
	s_add_i32 s54, s44, 1
	s_cmp_lg_u32 s44, 2
	s_cselect_b32 s67, s54, 0
	s_waitcnt vmcnt(0)
	s_barrier
	s_lshl_b32 s66, s67, 14
	s_add_i32 s54, s81, s66
	v_lshl_add_u64 v[4:5], v[190:191], 0, s[52:53]
	s_mov_b32 m0, s54
	s_add_i32 s52, s71, s82
	global_load_lds_dwordx4 v[4:5], off
	v_lshl_add_u64 v[4:5], v[4:5], 0, s[14:15]
	s_add_i32 m0, s54, 0x2000
	s_add_i32 s52, s52, s27
	global_load_lds_dwordx4 v[4:5], off
	s_add_i32 m0, s52, 0xc000
	s_cmp_ge_u32 s45, s2
	s_cselect_b64 s[52:53], -1, 0
	s_cmp_lt_u32 s45, s2
	s_cselect_b32 s54, s45, s3
	s_lshl_b32 s54, s54, 6
	v_mad_u64_u32 v[4:5], s[54:55], s54, v209, v[192:193]
	v_lshl_add_u64 v[4:5], v[4:5], 0, s[10:11]
	global_load_lds_dwordx4 v[4:5], off
	v_cvt_f32_u32_e32 v1, s65
	s_mul_i32 s54, s44, 0x2100
	s_add_i32 s54, s54, 0
	v_add_u32_e32 v166, s54, v220
	v_sub_f32_e32 v196, v1, v161
	v_add_u32_e32 v167, s54, v217
	v_fma_f32 v1, v210, v196, -v221
	ds_read_b128 v[4:7], v166 offset:49152
	ds_read_b128 v[8:11], v167 offset:49152
	v_and_b32_e32 v2, 0xffff0000, v1
	v_sub_f32_e32 v1, v1, v2
	v_and_b32_e32 v12, 0xffff0000, v1
	v_sub_f32_e32 v1, v1, v12
	v_perm_b32 v12, v12, v2, s99
	v_lshrrev_b32_e32 v2, 16, v1
	v_mov_b32_e32 v1, v12
	s_nop 1
	v_mfma_f32_32x32x16_bf16 v[128:143], v[248:251], v[0:3], 0
	v_add_f32_e32 v226, v96, v97
	v_add_f32_e32 v226, v98, v226
	v_add_f32_e32 v226, v99, v226
	v_add_f32_e32 v226, v100, v226
	s_nop 0
	v_mfma_f32_32x32x16_bf16 v[112:127], v[252:255], v[0:3], 0
	v_add_f32_e32 v1, v101, v226
	v_add_f32_e32 v1, v102, v1
	s_waitcnt lgkmcnt(0)
	v_mfma_f32_32x32x16_bf16 v[128:143], v[8:11], v[156:159], v[128:143]
	v_add_f32_e32 v1, v103, v1
	v_add_f32_e32 v1, v104, v1
	v_add_f32_e32 v1, v105, v1
	v_add_f32_e32 v1, v106, v1
	v_add_f32_e32 v1, v107, v1
	v_add_f32_e32 v1, v108, v1
	v_add_f32_e32 v1, v109, v1
	v_mfma_f32_32x32x16_bf16 v[112:127], v[4:7], v[156:159], v[112:127]
	ds_read_b128 v[4:7], v166 offset:51264
	ds_read_b128 v[8:11], v167 offset:51264
	v_add_f32_e32 v1, v110, v1
	v_add_f32_e32 v1, v111, v1
	v_add_f32_e32 v1, v80, v1
	v_add_f32_e32 v1, v81, v1
	v_add_f32_e32 v1, v82, v1
	v_add_f32_e32 v1, v83, v1
	s_waitcnt lgkmcnt(0)
	v_mfma_f32_32x32x16_bf16 v[128:143], v[8:11], v[152:155], v[128:143]
	v_add_f32_e32 v1, v84, v1
	v_add_f32_e32 v1, v85, v1
	v_add_f32_e32 v1, v86, v1
	v_add_f32_e32 v1, v87, v1
	v_add_f32_e32 v1, v88, v1
	v_add_f32_e32 v1, v89, v1
	v_add_f32_e32 v1, v90, v1
	v_mfma_f32_32x32x16_bf16 v[112:127], v[4:7], v[152:155], v[112:127]
	ds_read_b128 v[4:7], v166 offset:53376
	ds_read_b128 v[8:11], v167 offset:53376
	v_add_f32_e32 v1, v91, v1
	v_add_f32_e32 v1, v92, v1
	v_add_f32_e32 v1, v93, v1
	v_add_f32_e32 v1, v94, v1
	v_add_f32_e32 v1, v95, v1
	v_mov_b32_e32 v2, v1
	s_waitcnt lgkmcnt(0)
	v_mfma_f32_32x32x16_bf16 v[128:143], v[8:11], v[148:151], v[128:143]
	v_permlane32_swap_b32_e32 v1, v2
	v_mfma_f32_32x32x16_bf16 v[112:127], v[4:7], v[148:151], v[112:127]
	ds_read_b128 v[4:7], v166 offset:55488
	ds_read_b128 v[8:11], v167 offset:55488
	v_cvt_pk_bf16_f32 v166, v96, v97
	v_cvt_pk_bf16_f32 v167, v98, v99
	v_cvt_pk_bf16_f32 v168, v100, v101
	v_cvt_pk_bf16_f32 v169, v102, v103
	v_cvt_pk_bf16_f32 v12, v104, v105
	v_cvt_pk_bf16_f32 v13, v106, v107
	s_waitcnt lgkmcnt(0)
	v_mfma_f32_32x32x16_bf16 v[128:143], v[8:11], v[144:147], v[128:143]
	v_cvt_pk_bf16_f32 v14, v108, v109
	v_cvt_pk_bf16_f32 v15, v110, v111
	v_cvt_pk_bf16_f32 v8, v80, v81
	v_cvt_pk_bf16_f32 v9, v82, v83
	v_cvt_pk_bf16_f32 v10, v84, v85
	v_cvt_pk_bf16_f32 v11, v86, v87
	v_mfma_f32_32x32x16_bf16 v[112:127], v[4:7], v[144:147], v[112:127]
	v_cvt_pk_bf16_f32 v4, v88, v89
	v_cvt_pk_bf16_f32 v5, v90, v91
	v_cvt_pk_bf16_f32 v6, v92, v93
	v_cvt_pk_bf16_f32 v7, v94, v95
	v_lshl_add_u32 v162, s69, 14, v215
	ds_read_b64_tr_b16 v[182:183], v162 offset:0
	ds_read_b64_tr_b16 v[184:185], v162 offset:0x800
	ds_read_b64_tr_b16 v[178:179], v162 offset:0x1000
	ds_read_b64_tr_b16 v[180:181], v162 offset:0x1800
	s_add_i32 s54, s64, s45
	ds_read_b64_tr_b16 v[174:175], v162 offset:0x2000
	s_cmp_eq_u32 s54, 4
	ds_read_b64_tr_b16 v[176:177], v162 offset:0x2800
	s_cselect_b64 s[54:55], -1, 0
	ds_read_b64_tr_b16 v[170:171], v162 offset:0x3000
	v_cndmask_b32_e64 v80, 0, 1, s[54:55]
	ds_read_b64_tr_b16 v[172:173], v162 offset:0x3800
	s_add_i32 s98, s70, 2
	s_cmp_le_i32 s98, s31
	s_cbranch_scc0 .Lold_even
	v_max3_f32 v245, v128, v129, v130
	v_max3_f32 v246, v112, v113, v114
	v_max3_f32 v245, v245, v131, v132
	v_max3_f32 v246, v246, v115, v116
	v_max3_f32 v245, v245, v133, v134
	v_max3_f32 v246, v246, v117, v118
	v_max3_f32 v245, v245, v135, v136
	v_max3_f32 v246, v246, v119, v120
	v_max3_f32 v245, v245, v137, v138
	v_max3_f32 v246, v246, v121, v122
	v_max3_f32 v245, v245, v139, v140
	v_max3_f32 v246, v246, v123, v124
	v_max3_f32 v245, v245, v141, v142
	v_max3_f32 v246, v246, v125, v126
	v_max_f32_e32 v245, v245, v143
	v_max_f32_e32 v246, v246, v127
	v_max_f32_e32 v245, v245, v246
	v_mov_b32_e32 v246, v245
	s_nop 1
	v_permlane32_swap_b32_e32 v245, v246
	v_max_f32_e32 v245, v245, v246
	v_cmp_ge_f32_e32 vcc, s68, v245
	s_cmp_eq_u64 vcc, exec
	v_mov_b32_e32 v196, 1.0
	s_cbranch_scc0 .Lf_even_resc
